# in-proj slack late start + gate-prep phase started in 4 groups 1.8 us apart
# baseline (speedup 1.0000x reference)
; __global__ void __launch_bounds__(512, 2) fwd_megakernel(Params p) {
;     ...
;         { const int ntile = (l == 0) ? (NROW / 128) * 4 : (NLAT / 128) * 4;
;           const int nextra = (G > 128 && ntile > SGU_IN_M2) ? ntile - SGU_IN_M2 : 0;
;           for (int it = bid; it < 32 * NCH + nextra; it += G) { if (it < 32 * NCH) prep_item(p, l, 32 * NCH - 1 - it, lds); else sgu_tile(p, l, SGU_IN_M2 + it - 32 * NCH, lds); } }
.LBB0_240:
	s_or_b64 exec, exec, s[0:1]
	v_readlane_b32 s0, v243, 41
	v_readlane_b32 s1, v243, 42
	s_andn2_b64 vcc, exec, s[0:1]
	s_waitcnt lgkmcnt(0)
	s_barrier
	s_cbranch_vccnz .LBB0_319
	s_cmp_lg_u32 s46, 0x100
	s_cbranch_scc1 .Ldsprep_x
	s_bfe_u32 s98, s92, 0x20003
	s_lshl_b32 s98, s98, 3
	s_cmp_eq_u32 s98, 0
	s_cbranch_scc1 .Ldsprep_x
	s_min_u32 s98, s98, 32

; __device__ __forceinline__ int opaque_tid() { int t = threadIdx.x; asm volatile("" : "+v"(t)); return t; }
; __device__ void prep_item(const Params& p, int l, int item, LAS unsigned char* lds) {
;     const int tid = opaque_tid(), w = tid >> 6, lane = tid & 63;
;     const int tau = lane & 31, kh = lane >> 5, k0 = 16 * w + 8 * kh, l15 = lane & 15, q4 = lane >> 4;
;     const int ci = item % NCH, bh = item / NCH, h = bh & 3, b = bh >> 2;
;     const int R0 = ci < 8 ? NLAT + b * 256 + 32 * ci : b * 4096 + 32 * (ci - 8);
.Ldsprep_x:
	v_readlane_b32 s0, v240, 24
	v_readlane_b32 s1, v240, 25
	s_bitcmp1_b32 s0, 0
	s_cselect_b64 s[0:1], -1, 0
	s_xor_b64 s[88:89], s[0:1], -1
	v_readlane_b32 s2, v240, 12
	s_mov_b32 s5, s92
	v_and_b32_e32 v212, 31, v135
	v_lshrrev_b32_e32 v214, 5, v135
	v_lshlrev_b32_e32 v213, 4, v214
	v_lshlrev_b32_e32 v214, 5, v214
	v_sub_u32_e32 v215, 31, v212
	v_lshl_add_u32 v212, v212, 8, v213
	v_lshl_add_u32 v213, v215, 8, v213
	s_mov_b32 s98, s2
	s_mul_hi_u32 s99, s98, 0xf0f0f0f1
	s_lshr_b32 s100, s99, 7
	s_mul_i32 s101, s100, 0x88
	s_sub_i32 s98, s98, s101
	s_lshr_b32 s99, s99, 9
	s_and_b32 s100, s100, 3
	s_lshl_b32 s101, s98, 5
	s_cmp_gt_u32 s98, 7
	s_cbranch_scc1 .Lpf_lat_a
	s_lshl_b32 s99, s99, 8
	s_add_i32 s101, s101, 0x8000
	s_branch .Lpf_join_a
